# S5 item Kt tail: skip term D loaded once before the loop and added via v_cndmask (was eight serial predicated load-and-wait blocks), Kt stored with two ds_write_b128
# baseline (speedup 1.0000x reference)
.Lssa_471:
	global_load_dword v48, v[4:5], off
	global_load_dword v49, v[6:7], off
	v_add_co_u32_e32 v37, vcc, 0x200, v37
	s_xor_b64 s[84:85], vcc, -1
	s_and_b64 s[84:85], exec, s[84:85]
	v_lshl_add_u64 v[6:7], v[6:7], 0, s[80:81]
	v_lshl_add_u64 v[4:5], v[4:5], 0, s[80:81]
	s_or_b64 s[4:5], s[84:85], s[4:5]
	s_waitcnt vmcnt(0)
	ds_write_b64 v8, v[48:49]
	v_add_u32_e32 v8, 0x1000, v8
	s_andn2_b64 exec, exec, s[4:5]
	s_cbranch_execnz .Lssa_471
	s_or_b64 exec, exec, s[4:5]
	v_mov_b32_e32 v4, 0
	s_mov_b32 s4, 0
	v_mov_b32_e32 v8, v77
	v_mov_b32_e32 v5, v4
	v_mov_b32_e32 v50, v4
	v_mov_b32_e32 v51, v4
	v_mov_b32_e32 v48, v4
	v_mov_b32_e32 v49, v4
	v_mov_b32_e32 v6, v4
	v_mov_b32_e32 v7, v4
	v_mov_b32_e32 v112, v4
	v_mov_b32_e32 v113, v4
	v_mov_b32_e32 v114, v4
	v_mov_b32_e32 v115, v4
	v_mov_b32_e32 v116, v4
	v_mov_b32_e32 v117, v4
	v_mov_b32_e32 v118, v4
	v_mov_b32_e32 v119, v4
	s_load_dwordx2 s[84:85], s[22:23], 0x80
	v_bfe_u32 v14, v208, 1, 4
	v_lshl_add_u32 v14, s82, 4, v14
	v_lshlrev_b32_e32 v14, 2, v14
	s_waitcnt lgkmcnt(0)
	global_load_dword v14, v14, s[84:85]
	v_and_b32_e32 v12, 14, v208
	v_lshlrev_b32_e32 v12, 3, v12
	s_waitcnt lgkmcnt(0)
	s_barrier
.Lssa_473:
	v_add_u32_e32 v44, s4, v67
	v_add_u32_e32 v37, s4, v76
	v_xor_b32_e32 v37, v12, v37
	ds_read_b128 v[102:105], v44
	ds_read_b128 v[106:109], v37
	ds_read_b128 v[52:55], v8
	ds_read_b128 v[56:59], v8 offset:16
	ds_read_b128 v[60:63], v8 offset:32
	ds_read_b128 v[82:85], v8 offset:48
	ds_read_b128 v[86:89], v8 offset:128
	ds_read_b128 v[90:93], v8 offset:144
	ds_read_b128 v[94:97], v8 offset:160
	ds_read_b128 v[98:101], v8 offset:176
	s_waitcnt lgkmcnt(8)
	v_pk_mul_f32 v[110:111], v[106:107], v[102:103] op_sel:[1,1] op_sel_hi:[0,1]
	v_pk_fma_f32 v[110:111], v[106:107], v[102:103], v[110:111] op_sel_hi:[1,0,1] neg_lo:[0,0,1]
	s_waitcnt lgkmcnt(7)
	v_pk_fma_f32 v[112:113], v[110:111], v[52:53], v[112:113]
	v_pk_fma_f32 v[114:115], v[110:111], v[54:55], v[114:115]
	s_waitcnt lgkmcnt(6)
	v_pk_fma_f32 v[116:117], v[110:111], v[56:57], v[116:117]
	v_pk_fma_f32 v[118:119], v[110:111], v[58:59], v[118:119]
	s_waitcnt lgkmcnt(5)
	v_pk_fma_f32 v[48:49], v[110:111], v[60:61], v[48:49]
	v_pk_fma_f32 v[50:51], v[110:111], v[62:63], v[50:51]
	s_waitcnt lgkmcnt(4)
	v_pk_fma_f32 v[4:5], v[110:111], v[82:83], v[4:5]
	v_pk_fma_f32 v[6:7], v[110:111], v[84:85], v[6:7]
	v_pk_mul_f32 v[110:111], v[108:109], v[104:105] op_sel:[1,1] op_sel_hi:[0,1]
	v_pk_fma_f32 v[110:111], v[108:109], v[104:105], v[110:111] op_sel_hi:[1,0,1] neg_lo:[0,0,1]
	s_waitcnt lgkmcnt(3)
	v_pk_fma_f32 v[112:113], v[110:111], v[86:87], v[112:113]
	v_pk_fma_f32 v[114:115], v[110:111], v[88:89], v[114:115]
	s_waitcnt lgkmcnt(2)
	v_pk_fma_f32 v[116:117], v[110:111], v[90:91], v[116:117]
	v_pk_fma_f32 v[118:119], v[110:111], v[92:93], v[118:119]
	s_waitcnt lgkmcnt(1)
	v_pk_fma_f32 v[48:49], v[110:111], v[94:95], v[48:49]
	v_pk_fma_f32 v[50:51], v[110:111], v[96:97], v[50:51]
	s_waitcnt lgkmcnt(0)
	v_pk_fma_f32 v[4:5], v[110:111], v[98:99], v[4:5]
	v_pk_fma_f32 v[6:7], v[110:111], v[100:101], v[6:7]
	s_add_i32 s4, s4, 16
	v_add_u32_e32 v8, 0x100, v8
	s_cmpk_eq_i32 s4, 0x200
	s_cbranch_scc0 .Lssa_473
	s_waitcnt vmcnt(0)
	v_sub_f32_e32 v52, v112, v113
	v_sub_f32_e32 v53, v114, v115
	v_sub_f32_e32 v54, v116, v117
	v_sub_f32_e32 v55, v118, v119
	v_sub_f32_e32 v56, v48, v49
	v_sub_f32_e32 v57, v50, v51
	v_sub_f32_e32 v58, v4, v5
	v_sub_f32_e32 v59, v6, v7
	v_cndmask_b32_e64 v60, 0, v14, s[42:43]
	v_add_f32_e32 v52, v52, v60
	v_cndmask_b32_e64 v60, 0, v14, s[44:45]
	v_add_f32_e32 v53, v53, v60
	v_cndmask_b32_e64 v60, 0, v14, s[46:47]
	v_add_f32_e32 v54, v54, v60
	v_cndmask_b32_e64 v60, 0, v14, s[48:49]
	v_add_f32_e32 v55, v55, v60
	v_cndmask_b32_e64 v60, 0, v14, s[50:51]
	v_add_f32_e32 v56, v56, v60
	v_cndmask_b32_e64 v60, 0, v14, s[52:53]
	v_add_f32_e32 v57, v57, v60
	v_cndmask_b32_e64 v60, 0, v14, s[54:55]
	v_add_f32_e32 v58, v58, v60
	v_cndmask_b32_e64 v60, 0, v14, s[56:57]
	v_add_f32_e32 v59, v59, v60
	s_lshl_b32 s86, s97, 6
	s_lshl_b32 s87, s82, 8
	s_mov_b32 s91, 0
	ds_write_b128 v69, v[52:55] offset:25088
	ds_write_b128 v69, v[56:59] offset:25104
	s_waitcnt lgkmcnt(0)
	s_barrier
	s_branch .Lssa_493
